# tile order: groups of 4 row panels in P1, P3, P6 (was 2) + v_mov_b64 accumulator zeroing
# speedup vs baseline: 1.0087x; 1.0051x over previous
.LBB0_276:
	s_or_b64 exec, exec, s[0:1]
	v_mov_b32_e32 v8, v242
	s_cmpk_lt_i32 s2, 0x500
	s_waitcnt lgkmcnt(0)
	s_barrier
	s_cselect_b64 s[0:1], -1, 0
	s_cmpk_gt_i32 s2, 0x4ff
	v_readfirstlane_b32 s4, v8
	s_cbranch_scc1 .LBB0_278
	s_ashr_i32 s5, s2, 31
	s_lshr_b32 s5, s5, 29
	s_add_i32 s5, s2, s5
	s_ashr_i32 s6, s5, 3
	s_and_b32 s5, s5, -8
	s_sub_i32 s5, s2, s5
	s_cmp_lt_i32 s5, 0
	s_movk_i32 s7, 0xa1
	s_cselect_b32 s7, s7, 0xa0
	s_mul_i32 s5, s5, s7
	s_add_i32 s5, s5, s6
	s_mul_i32 s6, s5, 0x667
	s_lshr_b32 s6, s6, 16
	s_mul_i32 s7, s6, 40
	s_sub_i32 s5, s5, s7
	s_and_b32 s7, s5, 3
	s_lshl_b32 s6, s6, 2
	s_add_i32 s56, s7, s6
	s_lshr_b32 s6, s5, 2

.LBB0_284:
	s_add_i32 s79, s79, 1
	s_mul_i32 s4, s79, s85
	s_mul_hi_u32 s5, s79, s86
	s_add_i32 s5, s5, s4
	s_mul_i32 s4, s79, s86
	s_add_u32 s52, s4, s2
	s_addc_u32 s53, s5, s87
	v_cmp_gt_i64_e32 vcc, s[52:53], v[162:163]
	v_cmp_lt_i64_e64 s[4:5], s[52:53], v[160:161]
	s_cbranch_vccnz .LBB0_286
	s_and_b32 s16, s52, 7
	s_lshr_b32 s17, s52, 3
	s_mul_i32 s16, s16, 0xa0
	s_add_i32 s16, s16, s17
	s_mul_i32 s17, s16, 0x667
	s_lshr_b32 s17, s17, 16
	s_mul_i32 s18, s17, 40
	s_sub_i32 s16, s16, s18
	s_and_b32 s18, s16, 3
	s_lshl_b32 s17, s17, 2
	s_add_i32 s18, s18, s17
	s_lshr_b32 s16, s16, 2
